# s5_scan input loads prefetched 16 steps ahead; kmat processes two g per iteration with 18 loads in flight
# speedup vs baseline: 1.0173x; 1.0055x over previous
; __device__ __forceinline__ int obid() { int t = blockIdx.x; asm volatile("" : "+s"(t)); return t; }
; __device__ __forceinline__ unsigned pack2(float lo, float hi) { const f32x2_t v = {lo, hi}; const bf16x2_t b = __builtin_convertvector(v, bf16x2_t); return __builtin_bit_cast(unsigned, b); }
; __device__ void phase_s5_scan(CP P) {
;     ...
;     for (int idx = obid() * 128 + tid_; idx < 32 * 8 * 2 * 64; idx += gridDim.x * 128) {
;         const int n = idx & 63, dir = (idx >> 6) & 1, b = (idx >> 7) & 7, g = idx >> 10;
;         const float ar = AT[((g * 2 + dir) * 64 + n) * 2], ai = AT[((g * 2 + dir) * 64 + n) * 2 + 1];
;         float xr = 0.f, xi = 0.f;
; #pragma unroll 1
;         for (int c0 = 0; c0 < 128; c0 += 16) { float2 ev[16];
; #pragma unroll
;             for (int k = 0; k < 16; ++k) { const int c = dir == 0 ? c0 + k : 127 - (c0 + k); const size_t bc = (size_t)g * 1024 + b * 128 + c; ev[k] = *(const float2*)(E + bc * 256 + dir * 128 + n * 2); }
; #pragma unroll
;             for (int k = 0; k < 16; ++k) { const int c = dir == 0 ? c0 + k : 127 - (c0 + k); const size_t bc = (size_t)g * 1024 + b * 128 + c;
;                 *(unsigned*)(AS5 + bc * 1280 + 1024 + dir * 128 + n * 2) = pack2(xr, xi);
;                 const float t0 = ar * xr - ai * xi + ev[k].x; xi = ar * xi + ai * xr + ev[k].y; xr = t0; } }
.LBB0_157:
	v_bfe_u32 v3, v76, 6, 1
	v_ashrrev_i32_e32 v6, 10, v76
	v_lshlrev_b32_e32 v4, 7, v6
	v_lshlrev_b32_e32 v5, 6, v3
	v_or3_b32 v4, v5, v4, v77
	v_lshlrev_b32_e32 v4, 1, v4
	v_readlane_b32 s12, v255, 0
	v_ashrrev_i32_e32 v5, 31, v4
	v_readlane_b32 s13, v255, 1
	v_ashrrev_i32_e32 v7, 31, v6
	v_mov_b32_e32 v9, v184
	v_lshl_add_u64 v[4:5], v[4:5], 2, s[12:13]
	global_load_dwordx2 v[4:5], v[4:5], off
	v_mov_b32_e32 v14, 0
	v_lshlrev_b32_e32 v10, 7, v3
	v_lshlrev_b32_e32 v8, 9, v3
	v_lshlrev_b64 v[6:7], 10, v[6:7]
	s_movk_i32 s13, 0x380
	s_mov_b32 s11, 0
	s_movk_i32 s12, 0x70
	v_cmp_eq_u32_e64 s[40:41], 0, v3
	v_lshlrev_b32_e32 v98, 9, v3
	v_lshl_add_u32 v98, v77, 3, v98
	v_mov_b32_e32 v99, 0xfffffc00
	v_mov_b32_e32 v97, 0x400
	v_cndmask_b32_e64 v99, v99, v97, s[40:41]
	v_lshl_add_u64 v[8:9], v[0:1], 0, v[8:9]
	v_lshlrev_b32_e32 v10, 1, v10
	v_and_or_b32 v6, v76, s13, v6
	v_mov_b32_e32 v15, v14
	s_waitcnt vmcnt(0)
	v_pk_mov_b32 v[12:13], v[4:5], v[4:5] op_sel:[1,0]
.LBB0_158:
	s_add_i32 s13, s12, 15
	v_mov_b32_e32 v3, s13
	v_mov_b32_e32 v11, s11
	v_cndmask_b32_e64 v16, v3, v11, s[40:41]
	v_add_u32_e32 v100, v6, v16
	v_lshl_add_u32 v100, v100, 10, v98
	global_load_dwordx2 v[102:103], v100, s[34:35]
	v_add_u32_e32 v100, v100, v99
	global_load_dwordx2 v[104:105], v100, s[34:35]
	v_add_u32_e32 v100, v100, v99
	global_load_dwordx2 v[106:107], v100, s[34:35]
	v_add_u32_e32 v100, v100, v99
	global_load_dwordx2 v[108:109], v100, s[34:35]
	v_add_u32_e32 v100, v100, v99
	global_load_dwordx2 v[110:111], v100, s[34:35]
	v_add_u32_e32 v100, v100, v99
	global_load_dwordx2 v[112:113], v100, s[34:35]
	v_add_u32_e32 v100, v100, v99
	global_load_dwordx2 v[114:115], v100, s[34:35]
	v_add_u32_e32 v100, v100, v99
	global_load_dwordx2 v[116:117], v100, s[34:35]
	v_add_u32_e32 v100, v100, v99
	global_load_dwordx2 v[118:119], v100, s[34:35]
	v_add_u32_e32 v100, v100, v99
	global_load_dwordx2 v[120:121], v100, s[34:35]
	v_add_u32_e32 v100, v100, v99
	global_load_dwordx2 v[122:123], v100, s[34:35]
	v_add_u32_e32 v100, v100, v99
	global_load_dwordx2 v[124:125], v100, s[34:35]
	v_add_u32_e32 v100, v100, v99
	global_load_dwordx2 v[126:127], v100, s[34:35]
	v_add_u32_e32 v100, v100, v99
	global_load_dwordx2 v[128:129], v100, s[34:35]
	v_add_u32_e32 v100, v100, v99
	global_load_dwordx2 v[130:131], v100, s[34:35]
	v_add_u32_e32 v100, v100, v99
	global_load_dwordx2 v[132:133], v100, s[34:35]
	v_mov_b32_e32 v17, v184
	v_lshl_add_u64 v[22:23], v[6:7], 0, v[16:17]
	v_lshlrev_b64 v[16:17], 10, v[22:23]
	v_lshl_add_u64 v[16:17], v[8:9], 0, v[16:17]
	s_add_i32 s13, s12, 14
	s_add_i32 s16, s11, 1
	v_mov_b32_e32 v3, s13
	v_mov_b32_e32 v11, s16
	v_cndmask_b32_e64 v18, v3, v11, s[40:41]
	v_mov_b32_e32 v19, v184
	v_lshl_add_u64 v[20:21], v[6:7], 0, v[18:19]
	v_lshlrev_b64 v[18:19], 10, v[20:21]
	v_lshl_add_u64 v[18:19], v[8:9], 0, v[18:19]
	s_add_i32 s13, s12, 13
	s_add_i32 s16, s11, 2
	v_mov_b32_e32 v3, s13
	v_mov_b32_e32 v11, s16
	s_add_i32 s13, s12, 12
	s_add_i32 s16, s11, 3
	v_cndmask_b32_e64 v24, v3, v11, s[40:41]
	v_mov_b32_e32 v3, s13
	v_mov_b32_e32 v11, s16
	s_add_i32 s13, s12, 11
	s_add_i32 s16, s11, 4
	v_cndmask_b32_e64 v28, v3, v11, s[40:41]
	v_mov_b32_e32 v3, s13
	v_mov_b32_e32 v11, s16
	s_add_i32 s13, s12, 10
	s_add_i32 s16, s11, 5
	v_cndmask_b32_e64 v32, v3, v11, s[40:41]
	v_mov_b32_e32 v3, s13
	v_mov_b32_e32 v11, s16
	s_add_i32 s13, s12, 9
	s_add_i32 s16, s11, 6
	v_cndmask_b32_e64 v36, v3, v11, s[40:41]
	v_mov_b32_e32 v3, s13
	v_mov_b32_e32 v11, s16
	s_add_i32 s13, s12, 8
	s_add_i32 s16, s11, 7
	v_cndmask_b32_e64 v40, v3, v11, s[40:41]
	v_mov_b32_e32 v3, s13
	v_mov_b32_e32 v11, s16
	s_add_i32 s13, s12, 7
	s_add_i32 s16, s11, 8
	v_cndmask_b32_e64 v44, v3, v11, s[40:41]
	v_mov_b32_e32 v3, s13
	v_mov_b32_e32 v11, s16
	s_add_i32 s13, s12, 6
	s_add_i32 s16, s11, 9
	v_cndmask_b32_e64 v48, v3, v11, s[40:41]
	v_mov_b32_e32 v3, s13
	v_mov_b32_e32 v11, s16
	s_add_i32 s13, s12, 5
	s_add_i32 s16, s11, 10
	v_cndmask_b32_e64 v52, v3, v11, s[40:41]
	v_mov_b32_e32 v3, s13
	v_mov_b32_e32 v11, s16
	s_add_i32 s13, s12, 4
	s_add_i32 s16, s11, 11
	v_cndmask_b32_e64 v56, v3, v11, s[40:41]
	v_mov_b32_e32 v3, s13
	v_mov_b32_e32 v11, s16
	s_add_i32 s13, s12, 3
	s_add_i32 s16, s11, 12
	v_cndmask_b32_e64 v60, v3, v11, s[40:41]
	v_mov_b32_e32 v3, s13
	v_mov_b32_e32 v11, s16
	s_add_i32 s13, s12, 2
	s_add_i32 s16, s11, 13
	v_cndmask_b32_e64 v64, v3, v11, s[40:41]
	v_mov_b32_e32 v3, s13
	v_mov_b32_e32 v11, s16
	s_add_i32 s16, s11, 14
	v_mov_b64_e32 v[82:83], s[94:95]
	v_cndmask_b32_e64 v68, v3, v11, s[40:41]
	s_add_i32 s13, s12, 1
	v_mov_b32_e32 v11, s16
	v_mad_u64_u32 v[84:85], s[16:17], v22, s74, v[82:83]
	v_mov_b32_e32 v3, s13
	s_add_i32 s13, s11, 15
	v_mov_b32_e32 v22, v85
	v_cndmask_b32_e64 v72, v3, v11, s[40:41]
	v_mov_b32_e32 v3, s12
	v_mov_b32_e32 v11, s13
	v_mad_u64_u32 v[22:23], s[16:17], v23, s74, v[22:23]
	v_cndmask_b32_e64 v78, v3, v11, s[40:41]
	v_mov_b32_e32 v85, v22
	v_mov_b32_e32 v11, v184
	v_lshl_add_u64 v[22:23], v[84:85], 0, v[10:11]
	v_pk_mul_f32 v[84:85], v[12:13], v[14:15] op_sel:[0,1]
	v_cvt_pk_bf16_f32 v88, v14, v15
	v_pk_fma_f32 v[86:87], v[4:5], v[14:15], v[84:85] neg_lo:[0,0,1] neg_hi:[0,0,1]
	v_pk_fma_f32 v[14:15], v[4:5], v[14:15], v[84:85] op_sel_hi:[1,0,1]
	v_mov_b32_e32 v25, v184
	v_mov_b32_e32 v87, v15
	s_waitcnt vmcnt(15)
	v_mov_b64_e32 v[16:17], v[102:103]
	v_pk_add_f32 v[14:15], v[86:87], v[16:17]
	v_mad_u64_u32 v[16:17], s[16:17], v20, s74, v[82:83]
	v_mov_b32_e32 v20, v17
	v_mad_u64_u32 v[20:21], s[16:17], v21, s74, v[20:21]
	v_mov_b32_e32 v17, v20
	v_pk_mul_f32 v[20:21], v[12:13], v[14:15] op_sel:[0,1]
	v_cvt_pk_bf16_f32 v86, v14, v15
	v_pk_fma_f32 v[84:85], v[4:5], v[14:15], v[20:21] neg_lo:[0,0,1] neg_hi:[0,0,1]
	v_pk_fma_f32 v[14:15], v[4:5], v[14:15], v[20:21] op_sel_hi:[1,0,1]
	v_lshl_add_u64 v[26:27], v[6:7], 0, v[24:25]
	v_mov_b32_e32 v85, v15
	s_waitcnt vmcnt(14)
; __device__ __forceinline__ int obid() { int t = blockIdx.x; asm volatile("" : "+s"(t)); return t; }
; __device__ __forceinline__ unsigned pack2(float lo, float hi) { const f32x2_t v = {lo, hi}; const bf16x2_t b = __builtin_convertvector(v, bf16x2_t); return __builtin_bit_cast(unsigned, b); }
; __device__ void phase_s5_scan(CP P) {
;     ...
;     for (int idx = obid() * 128 + tid_; idx < 32 * 8 * 2 * 64; idx += gridDim.x * 128) {
;         const int n = idx & 63, dir = (idx >> 6) & 1, b = (idx >> 7) & 7, g = idx >> 10;
;         const float ar = AT[((g * 2 + dir) * 64 + n) * 2], ai = AT[((g * 2 + dir) * 64 + n) * 2 + 1];
;         float xr = 0.f, xi = 0.f;
; #pragma unroll 1
;         for (int c0 = 0; c0 < 128; c0 += 16) { float2 ev[16];
; #pragma unroll
;             for (int k = 0; k < 16; ++k) { const int c = dir == 0 ? c0 + k : 127 - (c0 + k); const size_t bc = (size_t)g * 1024 + b * 128 + c; ev[k] = *(const float2*)(E + bc * 256 + dir * 128 + n * 2); }
; #pragma unroll
;             for (int k = 0; k < 16; ++k) { const int c = dir == 0 ? c0 + k : 127 - (c0 + k); const size_t bc = (size_t)g * 1024 + b * 128 + c;
;                 *(unsigned*)(AS5 + bc * 1280 + 1024 + dir * 128 + n * 2) = pack2(xr, xi);
;                 const float t0 = ar * xr - ai * xi + ev[k].x; xi = ar * xi + ai * xr + ev[k].y; xr = t0; } }
	v_mov_b64_e32 v[18:19], v[104:105]
	v_pk_add_f32 v[14:15], v[18:19], v[84:85]
	v_mad_u64_u32 v[18:19], s[16:17], v26, s74, v[82:83]
	v_lshlrev_b64 v[24:25], 10, v[26:27]
	v_mov_b32_e32 v20, v19
	v_lshl_add_u64 v[24:25], v[8:9], 0, v[24:25]
	v_mad_u64_u32 v[20:21], s[16:17], v27, s74, v[20:21]
	v_mov_b32_e32 v19, v20
	v_pk_mul_f32 v[24:25], v[12:13], v[14:15] op_sel:[0,1]
	v_mov_b32_e32 v29, v184
	v_cvt_pk_bf16_f32 v84, v14, v15
	v_pk_fma_f32 v[26:27], v[4:5], v[14:15], v[24:25] neg_lo:[0,0,1] neg_hi:[0,0,1]
	v_pk_fma_f32 v[14:15], v[4:5], v[14:15], v[24:25] op_sel_hi:[1,0,1]
	v_lshl_add_u64 v[30:31], v[6:7], 0, v[28:29]
	v_mov_b32_e32 v27, v15
	v_lshlrev_b64 v[28:29], 10, v[30:31]
	v_lshl_add_u64 v[28:29], v[8:9], 0, v[28:29]
	v_mov_b32_e32 v33, v184
	v_lshl_add_u64 v[34:35], v[6:7], 0, v[32:33]
	v_lshlrev_b64 v[32:33], 10, v[34:35]
	v_lshl_add_u64 v[32:33], v[8:9], 0, v[32:33]
	v_mov_b32_e32 v37, v184
	v_lshl_add_u64 v[38:39], v[6:7], 0, v[36:37]
	v_lshlrev_b64 v[36:37], 10, v[38:39]
	v_lshl_add_u64 v[36:37], v[8:9], 0, v[36:37]
	v_mov_b32_e32 v41, v184
	v_lshl_add_u64 v[42:43], v[6:7], 0, v[40:41]
	v_lshlrev_b64 v[40:41], 10, v[42:43]
	v_lshl_add_u64 v[40:41], v[8:9], 0, v[40:41]
	v_mov_b32_e32 v45, v184
	v_lshl_add_u64 v[46:47], v[6:7], 0, v[44:45]
	v_lshlrev_b64 v[44:45], 10, v[46:47]
	v_lshl_add_u64 v[44:45], v[8:9], 0, v[44:45]
	v_mov_b32_e32 v49, v184
	v_lshl_add_u64 v[50:51], v[6:7], 0, v[48:49]
	v_lshlrev_b64 v[48:49], 10, v[50:51]
	v_lshl_add_u64 v[48:49], v[8:9], 0, v[48:49]
	v_mov_b32_e32 v53, v184
	v_lshl_add_u64 v[54:55], v[6:7], 0, v[52:53]
	v_lshlrev_b64 v[52:53], 10, v[54:55]
	v_lshl_add_u64 v[52:53], v[8:9], 0, v[52:53]
	v_mov_b32_e32 v57, v184
	v_lshl_add_u64 v[58:59], v[6:7], 0, v[56:57]
	v_lshlrev_b64 v[56:57], 10, v[58:59]
	v_lshl_add_u64 v[56:57], v[8:9], 0, v[56:57]
	v_mov_b32_e32 v61, v184
	v_lshl_add_u64 v[62:63], v[6:7], 0, v[60:61]
	v_lshlrev_b64 v[60:61], 10, v[62:63]
	v_lshl_add_u64 v[60:61], v[8:9], 0, v[60:61]
	v_mov_b32_e32 v65, v184
	v_lshl_add_u64 v[66:67], v[6:7], 0, v[64:65]
	v_lshlrev_b64 v[64:65], 10, v[66:67]
	v_lshl_add_u64 v[64:65], v[8:9], 0, v[64:65]
	v_mov_b32_e32 v69, v184
	v_lshl_add_u64 v[70:71], v[6:7], 0, v[68:69]
	v_lshlrev_b64 v[68:69], 10, v[70:71]
	v_lshl_add_u64 v[68:69], v[8:9], 0, v[68:69]
	v_mov_b32_e32 v73, v184
	v_lshl_add_u64 v[74:75], v[6:7], 0, v[72:73]
	v_lshlrev_b64 v[72:73], 10, v[74:75]
	v_lshl_add_u64 v[72:73], v[8:9], 0, v[72:73]
	v_mov_b32_e32 v79, v184
	v_lshl_add_u64 v[78:79], v[6:7], 0, v[78:79]
	v_lshlrev_b64 v[80:81], 10, v[78:79]
	v_lshl_add_u64 v[80:81], v[8:9], 0, v[80:81]
	v_mov_b32_e32 v3, v184
	v_lshl_add_u64 v[22:23], v[22:23], 0, v[2:3]
	v_lshl_add_u64 v[16:17], v[16:17], 0, v[10:11]
	v_add_co_u32_e32 v22, vcc, s75, v22
	v_lshl_add_u64 v[16:17], v[16:17], 0, v[2:3]
	s_nop 0
	v_addc_co_u32_e32 v23, vcc, 0, v23, vcc
	v_lshl_add_u64 v[18:19], v[18:19], 0, v[10:11]
	v_add_co_u32_e32 v16, vcc, s75, v16
	v_lshl_add_u64 v[18:19], v[18:19], 0, v[2:3]
	s_nop 0
	v_addc_co_u32_e32 v17, vcc, 0, v17, vcc
	s_add_i32 s12, s12, -16
	s_add_i32 s13, s11, 16
	s_cmpk_gt_u32 s11, 0x6f
	s_mov_b32 s11, s13
	s_waitcnt vmcnt(13)
	v_mov_b64_e32 v[20:21], v[106:107]
	v_pk_add_f32 v[14:15], v[20:21], v[26:27]
	v_mad_u64_u32 v[20:21], s[16:17], v30, s74, v[82:83]
	v_mov_b32_e32 v24, v21
	v_mad_u64_u32 v[24:25], s[16:17], v31, s74, v[24:25]
	v_mov_b32_e32 v21, v24
	v_pk_mul_f32 v[26:27], v[12:13], v[14:15] op_sel:[0,1]
	v_cvt_pk_bf16_f32 v85, v14, v15
	v_pk_fma_f32 v[28:29], v[4:5], v[14:15], v[26:27] neg_lo:[0,0,1] neg_hi:[0,0,1]
	v_pk_fma_f32 v[14:15], v[4:5], v[14:15], v[26:27] op_sel_hi:[1,0,1]
	v_lshl_add_u64 v[20:21], v[20:21], 0, v[10:11]
	v_mov_b32_e32 v29, v15
	v_lshl_add_u64 v[20:21], v[20:21], 0, v[2:3]
	s_waitcnt vmcnt(12)
	v_mov_b64_e32 v[24:25], v[108:109]
	v_pk_add_f32 v[14:15], v[24:25], v[28:29]
	v_mad_u64_u32 v[24:25], s[16:17], v34, s74, v[82:83]
	v_mov_b32_e32 v26, v25
	v_mad_u64_u32 v[26:27], s[16:17], v35, s74, v[26:27]
	v_mov_b32_e32 v25, v26
	v_pk_mul_f32 v[28:29], v[12:13], v[14:15] op_sel:[0,1]
	v_cvt_pk_bf16_f32 v87, v14, v15
	v_pk_fma_f32 v[30:31], v[4:5], v[14:15], v[28:29] neg_lo:[0,0,1] neg_hi:[0,0,1]
	v_pk_fma_f32 v[14:15], v[4:5], v[14:15], v[28:29] op_sel_hi:[1,0,1]
	v_lshl_add_u64 v[24:25], v[24:25], 0, v[10:11]
	v_mov_b32_e32 v31, v15
	v_lshl_add_u64 v[24:25], v[24:25], 0, v[2:3]
	s_waitcnt vmcnt(11)
	v_mov_b64_e32 v[26:27], v[110:111]
	v_pk_add_f32 v[14:15], v[26:27], v[30:31]
	v_mad_u64_u32 v[26:27], s[16:17], v38, s74, v[82:83]
	v_mov_b32_e32 v28, v27
	v_mad_u64_u32 v[28:29], s[16:17], v39, s74, v[28:29]
	v_mov_b32_e32 v27, v28
	v_pk_mul_f32 v[30:31], v[12:13], v[14:15] op_sel:[0,1]
	v_cvt_pk_bf16_f32 v89, v14, v15
	v_pk_fma_f32 v[32:33], v[4:5], v[14:15], v[30:31] neg_lo:[0,0,1] neg_hi:[0,0,1]
	v_pk_fma_f32 v[14:15], v[4:5], v[14:15], v[30:31] op_sel_hi:[1,0,1]
	v_lshl_add_u64 v[26:27], v[26:27], 0, v[10:11]
	v_mov_b32_e32 v33, v15
	v_lshl_add_u64 v[26:27], v[26:27], 0, v[2:3]
	s_waitcnt vmcnt(10)
	v_mov_b64_e32 v[28:29], v[112:113]
	v_pk_add_f32 v[14:15], v[28:29], v[32:33]
	v_mad_u64_u32 v[28:29], s[16:17], v42, s74, v[82:83]
	v_mov_b32_e32 v30, v29
	v_mad_u64_u32 v[30:31], s[16:17], v43, s74, v[30:31]
	v_mov_b32_e32 v29, v30
	v_pk_mul_f32 v[32:33], v[12:13], v[14:15] op_sel:[0,1]
	v_cvt_pk_bf16_f32 v90, v14, v15
	v_pk_fma_f32 v[34:35], v[4:5], v[14:15], v[32:33] neg_lo:[0,0,1] neg_hi:[0,0,1]
	v_pk_fma_f32 v[14:15], v[4:5], v[14:15], v[32:33] op_sel_hi:[1,0,1]
	v_lshl_add_u64 v[28:29], v[28:29], 0, v[10:11]
	v_mov_b32_e32 v35, v15
	v_lshl_add_u64 v[28:29], v[28:29], 0, v[2:3]
	s_waitcnt vmcnt(9)
; __device__ __forceinline__ int obid() { int t = blockIdx.x; asm volatile("" : "+s"(t)); return t; }
; __device__ __forceinline__ unsigned pack2(float lo, float hi) { const f32x2_t v = {lo, hi}; const bf16x2_t b = __builtin_convertvector(v, bf16x2_t); return __builtin_bit_cast(unsigned, b); }
; __device__ void phase_s5_scan(CP P) {
;     ...
;     for (int idx = obid() * 128 + tid_; idx < 32 * 8 * 2 * 64; idx += gridDim.x * 128) {
;         const int n = idx & 63, dir = (idx >> 6) & 1, b = (idx >> 7) & 7, g = idx >> 10;
;         const float ar = AT[((g * 2 + dir) * 64 + n) * 2], ai = AT[((g * 2 + dir) * 64 + n) * 2 + 1];
;         float xr = 0.f, xi = 0.f;
; #pragma unroll 1
;         for (int c0 = 0; c0 < 128; c0 += 16) { float2 ev[16];
; #pragma unroll
;             for (int k = 0; k < 16; ++k) { const int c = dir == 0 ? c0 + k : 127 - (c0 + k); const size_t bc = (size_t)g * 1024 + b * 128 + c; ev[k] = *(const float2*)(E + bc * 256 + dir * 128 + n * 2); }
; #pragma unroll
;             for (int k = 0; k < 16; ++k) { const int c = dir == 0 ? c0 + k : 127 - (c0 + k); const size_t bc = (size_t)g * 1024 + b * 128 + c;
;                 *(unsigned*)(AS5 + bc * 1280 + 1024 + dir * 128 + n * 2) = pack2(xr, xi);
;                 const float t0 = ar * xr - ai * xi + ev[k].x; xi = ar * xi + ai * xr + ev[k].y; xr = t0; } }
	v_mov_b64_e32 v[30:31], v[114:115]
	v_pk_add_f32 v[14:15], v[30:31], v[34:35]
	v_mad_u64_u32 v[30:31], s[16:17], v46, s74, v[82:83]
	v_mov_b32_e32 v32, v31
	v_mad_u64_u32 v[32:33], s[16:17], v47, s74, v[32:33]
	v_mov_b32_e32 v31, v32
	v_pk_mul_f32 v[34:35], v[12:13], v[14:15] op_sel:[0,1]
	v_cvt_pk_bf16_f32 v91, v14, v15
	v_pk_fma_f32 v[36:37], v[4:5], v[14:15], v[34:35] neg_lo:[0,0,1] neg_hi:[0,0,1]
	v_pk_fma_f32 v[14:15], v[4:5], v[14:15], v[34:35] op_sel_hi:[1,0,1]
	v_lshl_add_u64 v[30:31], v[30:31], 0, v[10:11]
	v_mov_b32_e32 v37, v15
	v_lshl_add_u64 v[30:31], v[30:31], 0, v[2:3]
	s_waitcnt vmcnt(8)
	v_mov_b64_e32 v[32:33], v[116:117]
	v_pk_add_f32 v[14:15], v[32:33], v[36:37]
	v_mad_u64_u32 v[32:33], s[16:17], v50, s74, v[82:83]
	v_mov_b32_e32 v34, v33
	v_mad_u64_u32 v[34:35], s[16:17], v51, s74, v[34:35]
	v_mov_b32_e32 v33, v34
	v_pk_mul_f32 v[36:37], v[12:13], v[14:15] op_sel:[0,1]
	v_cvt_pk_bf16_f32 v92, v14, v15
	v_pk_fma_f32 v[38:39], v[4:5], v[14:15], v[36:37] neg_lo:[0,0,1] neg_hi:[0,0,1]
	v_pk_fma_f32 v[14:15], v[4:5], v[14:15], v[36:37] op_sel_hi:[1,0,1]
	v_lshl_add_u64 v[32:33], v[32:33], 0, v[10:11]
	v_mov_b32_e32 v39, v15
	v_lshl_add_u64 v[32:33], v[32:33], 0, v[2:3]
	s_waitcnt vmcnt(7)
	v_mov_b64_e32 v[34:35], v[118:119]
	v_pk_add_f32 v[14:15], v[34:35], v[38:39]
	v_mad_u64_u32 v[34:35], s[16:17], v54, s74, v[82:83]
	v_mov_b32_e32 v36, v35
	v_mad_u64_u32 v[36:37], s[16:17], v55, s74, v[36:37]
	v_mov_b32_e32 v35, v36
	v_pk_mul_f32 v[38:39], v[12:13], v[14:15] op_sel:[0,1]
	v_cvt_pk_bf16_f32 v93, v14, v15
	v_pk_fma_f32 v[40:41], v[4:5], v[14:15], v[38:39] neg_lo:[0,0,1] neg_hi:[0,0,1]
	v_pk_fma_f32 v[14:15], v[4:5], v[14:15], v[38:39] op_sel_hi:[1,0,1]
	v_lshl_add_u64 v[34:35], v[34:35], 0, v[10:11]
	v_mov_b32_e32 v41, v15
	v_lshl_add_u64 v[34:35], v[34:35], 0, v[2:3]
	s_waitcnt vmcnt(6)
	v_mov_b64_e32 v[36:37], v[120:121]
	v_pk_add_f32 v[14:15], v[36:37], v[40:41]
	v_mad_u64_u32 v[36:37], s[16:17], v58, s74, v[82:83]
	v_mov_b32_e32 v38, v37
	v_mad_u64_u32 v[38:39], s[16:17], v59, s74, v[38:39]
	v_mov_b32_e32 v37, v38
	v_pk_mul_f32 v[40:41], v[12:13], v[14:15] op_sel:[0,1]
	v_cvt_pk_bf16_f32 v52, v14, v15
	v_pk_fma_f32 v[42:43], v[4:5], v[14:15], v[40:41] neg_lo:[0,0,1] neg_hi:[0,0,1]
	v_pk_fma_f32 v[14:15], v[4:5], v[14:15], v[40:41] op_sel_hi:[1,0,1]
	v_lshl_add_u64 v[36:37], v[36:37], 0, v[10:11]
	v_mov_b32_e32 v43, v15
	v_lshl_add_u64 v[36:37], v[36:37], 0, v[2:3]
	s_waitcnt vmcnt(5)
	v_mov_b64_e32 v[38:39], v[122:123]
	v_pk_add_f32 v[14:15], v[38:39], v[42:43]
	v_mad_u64_u32 v[38:39], s[16:17], v62, s74, v[82:83]
	v_mov_b32_e32 v40, v39
	v_mad_u64_u32 v[40:41], s[16:17], v63, s74, v[40:41]
	v_mov_b32_e32 v39, v40
	v_pk_mul_f32 v[42:43], v[12:13], v[14:15] op_sel:[0,1]
	v_cvt_pk_bf16_f32 v53, v14, v15
	v_pk_fma_f32 v[44:45], v[4:5], v[14:15], v[42:43] neg_lo:[0,0,1] neg_hi:[0,0,1]
	v_pk_fma_f32 v[14:15], v[4:5], v[14:15], v[42:43] op_sel_hi:[1,0,1]
	v_lshl_add_u64 v[38:39], v[38:39], 0, v[10:11]
	v_mov_b32_e32 v45, v15
	v_lshl_add_u64 v[38:39], v[38:39], 0, v[2:3]
	s_waitcnt vmcnt(4)
	v_mov_b64_e32 v[40:41], v[124:125]
	v_pk_add_f32 v[14:15], v[40:41], v[44:45]
	v_mad_u64_u32 v[40:41], s[16:17], v66, s74, v[82:83]
	v_mov_b32_e32 v42, v41
	v_mad_u64_u32 v[42:43], s[16:17], v67, s74, v[42:43]
	v_mov_b32_e32 v41, v42
	v_pk_mul_f32 v[44:45], v[12:13], v[14:15] op_sel:[0,1]
	v_cvt_pk_bf16_f32 v54, v14, v15
	v_pk_fma_f32 v[46:47], v[4:5], v[14:15], v[44:45] neg_lo:[0,0,1] neg_hi:[0,0,1]
	v_pk_fma_f32 v[14:15], v[4:5], v[14:15], v[44:45] op_sel_hi:[1,0,1]
	v_lshl_add_u64 v[40:41], v[40:41], 0, v[10:11]
	v_mov_b32_e32 v47, v15
	v_lshl_add_u64 v[40:41], v[40:41], 0, v[2:3]
	s_waitcnt vmcnt(3)
; __device__ __forceinline__ int obid() { int t = blockIdx.x; asm volatile("" : "+s"(t)); return t; }
; __device__ __forceinline__ unsigned pack2(float lo, float hi) { const f32x2_t v = {lo, hi}; const bf16x2_t b = __builtin_convertvector(v, bf16x2_t); return __builtin_bit_cast(unsigned, b); }
; __device__ void phase_s5_scan(CP P) {
;     ...
;     for (int idx = obid() * 128 + tid_; idx < 32 * 8 * 2 * 64; idx += gridDim.x * 128) {
;         const int n = idx & 63, dir = (idx >> 6) & 1, b = (idx >> 7) & 7, g = idx >> 10;
;         const float ar = AT[((g * 2 + dir) * 64 + n) * 2], ai = AT[((g * 2 + dir) * 64 + n) * 2 + 1];
;         float xr = 0.f, xi = 0.f;
; #pragma unroll 1
;         for (int c0 = 0; c0 < 128; c0 += 16) { float2 ev[16];
; #pragma unroll
;             for (int k = 0; k < 16; ++k) { const int c = dir == 0 ? c0 + k : 127 - (c0 + k); const size_t bc = (size_t)g * 1024 + b * 128 + c; ev[k] = *(const float2*)(E + bc * 256 + dir * 128 + n * 2); }
; #pragma unroll
;             for (int k = 0; k < 16; ++k) { const int c = dir == 0 ? c0 + k : 127 - (c0 + k); const size_t bc = (size_t)g * 1024 + b * 128 + c;
;                 *(unsigned*)(AS5 + bc * 1280 + 1024 + dir * 128 + n * 2) = pack2(xr, xi);
;                 const float t0 = ar * xr - ai * xi + ev[k].x; xi = ar * xi + ai * xr + ev[k].y; xr = t0; } }
	v_mov_b64_e32 v[42:43], v[126:127]
	v_pk_add_f32 v[14:15], v[42:43], v[46:47]
	v_mad_u64_u32 v[42:43], s[16:17], v70, s74, v[82:83]
	v_mov_b32_e32 v44, v43
	v_mad_u64_u32 v[44:45], s[16:17], v71, s74, v[44:45]
	v_mov_b32_e32 v43, v44
	v_pk_mul_f32 v[46:47], v[12:13], v[14:15] op_sel:[0,1]
	v_cvt_pk_bf16_f32 v55, v14, v15
	v_pk_fma_f32 v[48:49], v[4:5], v[14:15], v[46:47] neg_lo:[0,0,1] neg_hi:[0,0,1]
	v_pk_fma_f32 v[14:15], v[4:5], v[14:15], v[46:47] op_sel_hi:[1,0,1]
	v_lshl_add_u64 v[42:43], v[42:43], 0, v[10:11]
	v_mov_b32_e32 v49, v15
	v_lshl_add_u64 v[42:43], v[42:43], 0, v[2:3]
	s_waitcnt vmcnt(2)
	v_mov_b64_e32 v[44:45], v[128:129]
	v_pk_add_f32 v[14:15], v[44:45], v[48:49]
	v_mad_u64_u32 v[44:45], s[16:17], v74, s74, v[82:83]
	v_mov_b32_e32 v46, v45
	v_mad_u64_u32 v[46:47], s[16:17], v75, s74, v[46:47]
	v_mov_b32_e32 v45, v46
	v_pk_mul_f32 v[48:49], v[12:13], v[14:15] op_sel:[0,1]
	v_cvt_pk_bf16_f32 v56, v14, v15
	v_pk_fma_f32 v[50:51], v[4:5], v[14:15], v[48:49] neg_lo:[0,0,1] neg_hi:[0,0,1]
	v_pk_fma_f32 v[14:15], v[4:5], v[14:15], v[48:49] op_sel_hi:[1,0,1]
	v_lshl_add_u64 v[44:45], v[44:45], 0, v[10:11]
	v_mov_b32_e32 v51, v15
	v_lshl_add_u64 v[44:45], v[44:45], 0, v[2:3]
	s_waitcnt vmcnt(1)
	v_mov_b64_e32 v[46:47], v[130:131]
	v_pk_add_f32 v[14:15], v[46:47], v[50:51]
	v_mad_u64_u32 v[46:47], s[16:17], v78, s74, v[82:83]
	v_mov_b32_e32 v48, v47
	v_mad_u64_u32 v[48:49], s[16:17], v79, s74, v[48:49]
	v_mov_b32_e32 v47, v48
	v_lshl_add_u64 v[46:47], v[46:47], 0, v[10:11]
	global_store_dword v[16:17], v86, off offset:2048
	v_add_co_u32_e32 v16, vcc, s75, v18
	global_store_dword v[22:23], v88, off offset:2048
	s_nop 0
	v_addc_co_u32_e32 v17, vcc, 0, v19, vcc
	global_store_dword v[16:17], v84, off offset:2048
	v_add_co_u32_e32 v16, vcc, s75, v20
	v_lshl_add_u64 v[46:47], v[46:47], 0, v[2:3]
	s_nop 0
	v_addc_co_u32_e32 v17, vcc, 0, v21, vcc
	global_store_dword v[16:17], v85, off offset:2048
	v_add_co_u32_e32 v16, vcc, s75, v24
	v_cvt_pk_bf16_f32 v50, v14, v15
	s_nop 0
	v_addc_co_u32_e32 v17, vcc, 0, v25, vcc
	global_store_dword v[16:17], v87, off offset:2048
	v_add_co_u32_e32 v16, vcc, s75, v26
	s_nop 1
	v_addc_co_u32_e32 v17, vcc, 0, v27, vcc
	global_store_dword v[16:17], v89, off offset:2048
	v_add_co_u32_e32 v16, vcc, s75, v28
	s_nop 1
	v_addc_co_u32_e32 v17, vcc, 0, v29, vcc
	global_store_dword v[16:17], v90, off offset:2048
	v_add_co_u32_e32 v16, vcc, s75, v30
	s_nop 1
	v_addc_co_u32_e32 v17, vcc, 0, v31, vcc
	global_store_dword v[16:17], v91, off offset:2048
	v_add_co_u32_e32 v16, vcc, s75, v32
	s_nop 1
	v_addc_co_u32_e32 v17, vcc, 0, v33, vcc
	global_store_dword v[16:17], v92, off offset:2048
	v_add_co_u32_e32 v16, vcc, s75, v34
	s_nop 1
	v_addc_co_u32_e32 v17, vcc, 0, v35, vcc
	global_store_dword v[16:17], v93, off offset:2048
	v_add_co_u32_e32 v16, vcc, s75, v36
	s_nop 1
	v_addc_co_u32_e32 v17, vcc, 0, v37, vcc
	global_store_dword v[16:17], v52, off offset:2048
	v_add_co_u32_e32 v16, vcc, s75, v38
	s_nop 1
	v_addc_co_u32_e32 v17, vcc, 0, v39, vcc
	global_store_dword v[16:17], v53, off offset:2048
	v_add_co_u32_e32 v16, vcc, s75, v40
	s_nop 1
	v_addc_co_u32_e32 v17, vcc, 0, v41, vcc
	global_store_dword v[16:17], v54, off offset:2048
	v_add_co_u32_e32 v16, vcc, s75, v42
	s_nop 1
	v_addc_co_u32_e32 v17, vcc, 0, v43, vcc
	global_store_dword v[16:17], v55, off offset:2048
	v_add_co_u32_e32 v16, vcc, s75, v44
	s_nop 1
	v_addc_co_u32_e32 v17, vcc, 0, v45, vcc
	global_store_dword v[16:17], v56, off offset:2048
	v_add_co_u32_e32 v16, vcc, s75, v46
	s_nop 1
	v_addc_co_u32_e32 v17, vcc, 0, v47, vcc
	global_store_dword v[16:17], v50, off offset:2048
	v_pk_mul_f32 v[16:17], v[12:13], v[14:15] op_sel:[0,1]
	s_nop 0
	v_pk_fma_f32 v[18:19], v[4:5], v[14:15], v[16:17] neg_lo:[0,0,1] neg_hi:[0,0,1]
	v_pk_fma_f32 v[14:15], v[4:5], v[14:15], v[16:17] op_sel_hi:[1,0,1]
	s_nop 0
	v_mov_b32_e32 v19, v15
	s_waitcnt vmcnt(16)
	v_mov_b64_e32 v[48:49], v[132:133]
	v_pk_add_f32 v[14:15], v[48:49], v[18:19]
	s_cbranch_scc0 .LBB0_158
	v_add_u32_e32 v76, s10, v76
	s_movk_i32 s11, 0x7fff
	v_cmp_lt_i32_e32 vcc, s11, v76
	s_or_b64 s[42:43], vcc, s[42:43]
	s_andn2_b64 exec, exec, s[42:43]
	s_cbranch_execnz .LBB0_157

; __device__ __forceinline__ int otid() { int t = threadIdx.x; asm volatile("" : "+v"(t)); return t; }
; __device__ __forceinline__ int obid() { int t = blockIdx.x; asm volatile("" : "+s"(t)); return t; }
; __device__ __forceinline__ unsigned pack2(float lo, float hi) { const f32x2_t v = {lo, hi}; const bf16x2_t b = __builtin_convertvector(v, bf16x2_t); return __builtin_bit_cast(unsigned, b); }
; __device__ void phase_kmat(CP P) {
;     ...
;     for (int idx = obid() * NTHR + otid(); idx < 32 * 1024 * 512; idx += gridDim.x * NTHR) {
;         const int kp = idx & 511, row = (idx >> 9) & 1023, g = idx >> 19, t = row >> 4, p = row & 15, k = kp * 2, s = k >> 4, pp = k & 15;
;         float v0 = 0.f, v1 = 0.f;
;         if (s <= t) { const float* b = Ktab + ((size_t)((g * 2 + 0) * 64 + (t - s))) * 256 + p * 16 + pp; v0 += b[0]; v1 += b[1]; }
;         if (s >= t) { const float* b = Ktab + ((size_t)((g * 2 + 1) * 64 + (s - t))) * 256 + p * 16 + pp; v0 += b[0]; v1 += b[1]; }
;         if (s == t) { const float dv = dsk[g * 16 + p]; if (pp == p) v0 += dv; if (pp + 1 == p) v1 += dv; }
;         *(unsigned*)(KG + ((size_t)(g * 1024 + row)) * 1280 + k) = pack2(v0, v1);
.LBB0_555:
	v_readlane_b32 s10, v254, 54
	v_readlane_b32 s11, v254, 55
	s_andn2_b64 vcc, exec, s[10:11]
	s_cbranch_vccnz .LBB0_566
	s_mov_b32 s10, s2
	v_mov_b32_e32 v0, v191
	s_mov_b64 s[20:21], exec
	v_readlane_b32 s16, v255, 2
	v_readlane_b32 s17, v255, 3
	v_readlane_b32 s26, v255, 6
	v_readlane_b32 s27, v255, 7
	s_load_dwordx2 s[12:13], s[0:1], 0x80
	v_mov_b32_e32 v185, v184
	v_mov_b32_e32 v96, 0
	v_lshrrev_b32_e32 v1, 3, v0
	v_lshlrev_b32_e32 v2, 1, v0
	v_and_b32_e32 v2, 14, v2
	v_or_b32_e32 v43, 1, v2
	s_and_b32 s24, s10, 15
	s_lshr_b32 s25, s10, 4
	s_lshl_b32 s11, s24, 6
	v_lshlrev_b32_e32 v3, 2, v2
	v_add_u32_e32 v3, s11, v3
	s_mulk_i32 s10, 0xa00
	v_lshl_add_u32 v44, v0, 2, s10
	s_add_i32 s11, s25, 0
	v_sub_u32_e32 v40, s11, v1
	v_max_i32_e32 v41, 0, v40
	v_sub_u32_e32 v42, 0, v40
	v_max_i32_e32 v42, 0, v42
	v_lshl_add_u32 v4, v41, 10, v3
	v_lshl_add_u32 v8, v42, 10, v3
	v_add_u32_e32 v8, 0x10000, v8
	v_cmp_le_i32_e32 vcc, 0, v40
	v_cmp_eq_u32_e64 s[22:23], 0, v40
	s_nop 1
	v_cndmask_b32_e64 v12, 0, 1.0, vcc
	v_cmp_ge_i32_e32 vcc, 0, v40
	s_nop 1
	v_cndmask_b32_e64 v13, 0, 1.0, vcc
	v_cmp_eq_u32_e32 vcc, s24, v2
	s_and_b64 vcc, vcc, s[22:23]
	v_cndmask_b32_e64 v20, 0, 1.0, vcc
	v_cmp_eq_u32_e32 vcc, s24, v43
	s_and_b64 vcc, vcc, s[22:23]
	v_cndmask_b32_e64 v21, 0, 1.0, vcc
	v_mov_b32_e32 v28, v44
	s_add_i32 s11, s25, 16
	v_sub_u32_e32 v40, s11, v1
	v_max_i32_e32 v41, 0, v40
	v_sub_u32_e32 v42, 0, v40
	v_max_i32_e32 v42, 0, v42
	v_lshl_add_u32 v5, v41, 10, v3
	v_lshl_add_u32 v9, v42, 10, v3
	v_add_u32_e32 v9, 0x10000, v9
	v_cmp_le_i32_e32 vcc, 0, v40
	v_cmp_eq_u32_e64 s[22:23], 0, v40
	s_nop 1
	v_cndmask_b32_e64 v14, 0, 1.0, vcc
	v_cmp_ge_i32_e32 vcc, 0, v40
	s_nop 1
	v_cndmask_b32_e64 v15, 0, 1.0, vcc
	v_cmp_eq_u32_e32 vcc, s24, v2
	s_and_b64 vcc, vcc, s[22:23]
	v_cndmask_b32_e64 v22, 0, 1.0, vcc
	v_cmp_eq_u32_e32 vcc, s24, v43
	s_and_b64 vcc, vcc, s[22:23]
	v_cndmask_b32_e64 v23, 0, 1.0, vcc
	v_add_u32_e32 v29, 0xa0000, v44
	s_add_i32 s11, s25, 32
	v_sub_u32_e32 v40, s11, v1
	v_max_i32_e32 v41, 0, v40
	v_sub_u32_e32 v42, 0, v40
	v_max_i32_e32 v42, 0, v42
	v_lshl_add_u32 v6, v41, 10, v3
	v_lshl_add_u32 v10, v42, 10, v3
	v_add_u32_e32 v10, 0x10000, v10
	v_cmp_le_i32_e32 vcc, 0, v40
	v_cmp_eq_u32_e64 s[22:23], 0, v40
	s_nop 1
	v_cndmask_b32_e64 v16, 0, 1.0, vcc
	v_cmp_ge_i32_e32 vcc, 0, v40
	s_nop 1
	v_cndmask_b32_e64 v17, 0, 1.0, vcc
	v_cmp_eq_u32_e32 vcc, s24, v2
	s_and_b64 vcc, vcc, s[22:23]
	v_cndmask_b32_e64 v24, 0, 1.0, vcc
	v_cmp_eq_u32_e32 vcc, s24, v43
	s_and_b64 vcc, vcc, s[22:23]
	v_cndmask_b32_e64 v25, 0, 1.0, vcc
	v_add_u32_e32 v30, 0x140000, v44
	s_add_i32 s11, s25, 48
	v_sub_u32_e32 v40, s11, v1
	v_max_i32_e32 v41, 0, v40
	v_sub_u32_e32 v42, 0, v40
	v_max_i32_e32 v42, 0, v42
	v_lshl_add_u32 v7, v41, 10, v3
	v_lshl_add_u32 v11, v42, 10, v3
	v_add_u32_e32 v11, 0x10000, v11
	v_cmp_le_i32_e32 vcc, 0, v40
	v_cmp_eq_u32_e64 s[22:23], 0, v40
	s_nop 1
	v_cndmask_b32_e64 v18, 0, 1.0, vcc
	v_cmp_ge_i32_e32 vcc, 0, v40
	s_nop 1
	v_cndmask_b32_e64 v19, 0, 1.0, vcc
	v_cmp_eq_u32_e32 vcc, s24, v2
	s_and_b64 vcc, vcc, s[22:23]
	v_cndmask_b32_e64 v26, 0, 1.0, vcc
	v_cmp_eq_u32_e32 vcc, s24, v43
	s_and_b64 vcc, vcc, s[22:23]
	v_cndmask_b32_e64 v27, 0, 1.0, vcc
	v_add_u32_e32 v31, 0x1e0000, v44
	s_waitcnt lgkmcnt(0)
	s_lshl_b32 s11, s24, 2
	s_add_u32 s12, s12, s11
	s_addc_u32 s13, s13, 0
	s_add_u32 s22, s16, 0x20000
	s_addc_u32 s23, s17, 0
	s_add_u32 s24, s26, 0x280000
	s_addc_u32 s25, s27, 0
	global_load_dword v60, v96, s[12:13]
	global_load_dwordx2 v[32:33], v4, s[16:17]
	global_load_dwordx2 v[34:35], v8, s[16:17]
	global_load_dwordx2 v[36:37], v5, s[16:17]
	global_load_dwordx2 v[38:39], v9, s[16:17]
	global_load_dwordx2 v[40:41], v6, s[16:17]
	global_load_dwordx2 v[42:43], v10, s[16:17]
	global_load_dwordx2 v[44:45], v7, s[16:17]
	global_load_dwordx2 v[46:47], v11, s[16:17]
	global_load_dword v62, v96, s[12:13] offset:64
	global_load_dwordx2 v[64:65], v4, s[22:23]
	global_load_dwordx2 v[66:67], v8, s[22:23]
	global_load_dwordx2 v[68:69], v5, s[22:23]
	global_load_dwordx2 v[70:71], v9, s[22:23]
	global_load_dwordx2 v[72:73], v6, s[22:23]
	global_load_dwordx2 v[74:75], v10, s[22:23]
	global_load_dwordx2 v[76:77], v7, s[22:23]
	global_load_dwordx2 v[78:79], v11, s[22:23]
	s_mov_b32 s11, 16
	s_waitcnt vmcnt(0)
	s_branch .Lkm_body

; __device__ __forceinline__ int otid() { int t = threadIdx.x; asm volatile("" : "+v"(t)); return t; }
; __device__ __forceinline__ int obid() { int t = blockIdx.x; asm volatile("" : "+s"(t)); return t; }
; __device__ __forceinline__ unsigned pack2(float lo, float hi) { const f32x2_t v = {lo, hi}; const bf16x2_t b = __builtin_convertvector(v, bf16x2_t); return __builtin_bit_cast(unsigned, b); }
; __device__ void phase_kmat(CP P) {
;     ...
;     for (int idx = obid() * NTHR + otid(); idx < 32 * 1024 * 512; idx += gridDim.x * NTHR) {
;         const int kp = idx & 511, row = (idx >> 9) & 1023, g = idx >> 19, t = row >> 4, p = row & 15, k = kp * 2, s = k >> 4, pp = k & 15;
;         float v0 = 0.f, v1 = 0.f;
;         if (s <= t) { const float* b = Ktab + ((size_t)((g * 2 + 0) * 64 + (t - s))) * 256 + p * 16 + pp; v0 += b[0]; v1 += b[1]; }
;         if (s >= t) { const float* b = Ktab + ((size_t)((g * 2 + 1) * 64 + (s - t))) * 256 + p * 16 + pp; v0 += b[0]; v1 += b[1]; }
;         if (s == t) { const float dv = dsk[g * 16 + p]; if (pp == p) v0 += dv; if (pp + 1 == p) v1 += dv; }
;         *(unsigned*)(KG + ((size_t)(g * 1024 + row)) * 1280 + k) = pack2(v0, v1);
.Lkm_body:
	v_pk_mul_f32 v[48:49], v[32:33], v[12:13] op_sel_hi:[1,0]
	v_pk_mul_f32 v[50:51], v[36:37], v[14:15] op_sel_hi:[1,0]
	v_pk_mul_f32 v[52:53], v[40:41], v[16:17] op_sel_hi:[1,0]
	v_pk_mul_f32 v[54:55], v[44:45], v[18:19] op_sel_hi:[1,0]
	v_pk_fma_f32 v[48:49], v[34:35], v[12:13], v[48:49] op_sel:[0,1,0] op_sel_hi:[1,1,1]
	v_pk_fma_f32 v[50:51], v[38:39], v[14:15], v[50:51] op_sel:[0,1,0] op_sel_hi:[1,1,1]
	v_pk_fma_f32 v[52:53], v[42:43], v[16:17], v[52:53] op_sel:[0,1,0] op_sel_hi:[1,1,1]
	v_pk_fma_f32 v[54:55], v[46:47], v[18:19], v[54:55] op_sel:[0,1,0] op_sel_hi:[1,1,1]
	v_pk_fma_f32 v[48:49], v[20:21], v[60:61], v[48:49] op_sel_hi:[1,0,1]
	v_pk_fma_f32 v[50:51], v[22:23], v[60:61], v[50:51] op_sel_hi:[1,0,1]
	v_pk_fma_f32 v[52:53], v[24:25], v[60:61], v[52:53] op_sel_hi:[1,0,1]
	v_pk_fma_f32 v[54:55], v[26:27], v[60:61], v[54:55] op_sel_hi:[1,0,1]
	v_cvt_pk_bf16_f32 v56, v48, v49
	v_cvt_pk_bf16_f32 v57, v50, v51
	v_cvt_pk_bf16_f32 v58, v52, v53
	v_cvt_pk_bf16_f32 v59, v54, v55
	v_pk_mul_f32 v[80:81], v[64:65], v[12:13] op_sel_hi:[1,0]
	v_pk_mul_f32 v[82:83], v[68:69], v[14:15] op_sel_hi:[1,0]
	v_pk_mul_f32 v[84:85], v[72:73], v[16:17] op_sel_hi:[1,0]
	v_pk_mul_f32 v[86:87], v[76:77], v[18:19] op_sel_hi:[1,0]
	v_pk_fma_f32 v[80:81], v[66:67], v[12:13], v[80:81] op_sel:[0,1,0] op_sel_hi:[1,1,1]
	v_pk_fma_f32 v[82:83], v[70:71], v[14:15], v[82:83] op_sel:[0,1,0] op_sel_hi:[1,1,1]
	v_pk_fma_f32 v[84:85], v[74:75], v[16:17], v[84:85] op_sel:[0,1,0] op_sel_hi:[1,1,1]
	v_pk_fma_f32 v[86:87], v[78:79], v[18:19], v[86:87] op_sel:[0,1,0] op_sel_hi:[1,1,1]
	v_pk_fma_f32 v[80:81], v[20:21], v[62:63], v[80:81] op_sel_hi:[1,0,1]
	v_pk_fma_f32 v[82:83], v[22:23], v[62:63], v[82:83] op_sel_hi:[1,0,1]
	v_pk_fma_f32 v[84:85], v[24:25], v[62:63], v[84:85] op_sel_hi:[1,0,1]
	v_pk_fma_f32 v[86:87], v[26:27], v[62:63], v[86:87] op_sel_hi:[1,0,1]
	v_cvt_pk_bf16_f32 v88, v80, v81
	v_cvt_pk_bf16_f32 v89, v82, v83
	v_cvt_pk_bf16_f32 v90, v84, v85
	v_cvt_pk_bf16_f32 v91, v86, v87
	s_add_u32 s16, s16, 0x40000
	s_addc_u32 s17, s17, 0
	s_add_u32 s22, s22, 0x40000
	s_addc_u32 s23, s23, 0
	s_add_u32 s12, s12, 0x80
	s_addc_u32 s13, s13, 0
	s_add_i32 s11, s11, -1
	s_cmp_lg_u32 s11, 0
	s_cbranch_scc0 .Lkm_st
	global_load_dword v60, v96, s[12:13]
	global_load_dwordx2 v[32:33], v4, s[16:17]
	global_load_dwordx2 v[34:35], v8, s[16:17]
	global_load_dwordx2 v[36:37], v5, s[16:17]
	global_load_dwordx2 v[38:39], v9, s[16:17]
	global_load_dwordx2 v[40:41], v6, s[16:17]
	global_load_dwordx2 v[42:43], v10, s[16:17]
	global_load_dwordx2 v[44:45], v7, s[16:17]
	global_load_dwordx2 v[46:47], v11, s[16:17]
	global_load_dword v62, v96, s[12:13] offset:64
	global_load_dwordx2 v[64:65], v4, s[22:23]
	global_load_dwordx2 v[66:67], v8, s[22:23]
	global_load_dwordx2 v[68:69], v5, s[22:23]
	global_load_dwordx2 v[70:71], v9, s[22:23]
	global_load_dwordx2 v[72:73], v6, s[22:23]
	global_load_dwordx2 v[74:75], v10, s[22:23]
	global_load_dwordx2 v[76:77], v7, s[22:23]
	global_load_dwordx2 v[78:79], v11, s[22:23]
.Lkm_st:
	global_store_dword v28, v56, s[26:27]
	global_store_dword v29, v57, s[26:27]
	global_store_dword v30, v58, s[26:27]
	global_store_dword v31, v59, s[26:27]
	global_store_dword v28, v88, s[24:25]
	global_store_dword v29, v89, s[24:25]
	global_store_dword v30, v90, s[24:25]
	global_store_dword v31, v91, s[24:25]
	s_add_u32 s26, s26, 0x500000
	s_addc_u32 s27, s27, 0
	s_add_u32 s24, s24, 0x500000
	s_addc_u32 s25, s25, 0
	s_cmp_lg_u32 s11, 0
	s_cbranch_scc1 .Lkm_loop
